# P1 work split: in-proj/KV GEMM units on 224 CUs in 6 near-full lockstep rounds; sample attention + late weight copies + state copies on the other 32 CUs concurrently
# speedup vs baseline: 1.1104x; 1.0282x over previous
;     __device__ __forceinline__ bool next(int i, Unit& u) const {
;         int L = i * G + c; if (L >= G1_ALL) return false;
;         u.nt = DM / 64; u.kind = 0;
;         if (L < G1_SPECIAL) { u.pm = MP / 256 + (L >> 3); u.pn = 30 + (L & 7); u.kind = 4; }
;         else if ((L -= G1_SPECIAL) < G1_PROMPT) { int pm, pn; pg8::tile_order(L, MP / 256, G1_NN, pm, pn); u.pm = pm; u.pn = pn; }
;         else if ((L -= G1_PROMPT) < G1_S2) { u.pm = MP / 256 + L / 30; u.pn = L % 30; }
;         else { const int r = L - G1_S2, t = r >> 4, pm = (r >> 2) & 3, pn = r & 3; u.pm = pm; u.pn = pn; u.kind = 1 + t;
;             if (t == 0) { u.A = HM + (size_t)pm * TSTEP4K; u.B = WKV + (size_t)pn * TSTEP4K; }
;             else if (t == 1) { u.A = HM + (size_t)pm * TSTEP4K; u.B = WKV + (size_t)(4 + pn) * TSTEP4K; }
;             else { u.A = WKV + (size_t)(4 + pm) * TSTEP4K; u.B = HM + (size_t)pn * TSTEP4K; }
;             return true; }
;         u.A = H + (size_t)u.pm * TSTEP4K; u.B = WIN + (size_t)u.pn * TSTEP4K;
;         return true;
; __global__ void __launch_bounds__(NTHR, 2) hybrid_fwd(Args args) {
;     ...
;       Sched1 S{F.G, (int)blockIdx.x, (const char*)(F.ws + WS_H), (const char*)(F.ws + WS_HM), (const char*)(F.ws + WS_WIN), (const char*)(F.ws + WS_WKV)};
;       Epi1 E{WSP(bf16_t, WS_U), WSP(bf16_t, WS_SGA), WSP(bf16_t, WS_A), WSP(bf16_t, WS_SGB), WSP(bf16_t, WS_Q), WSP(bf16_t, WS_SGC), WSP(bf16_t, WS_KP), WSP(bf16_t, WS_VPT), F.out + O_MK, F.out + O_MV, (unsigned*)(F.ws + WS_CTL) + CW_QREADY};
;       pg8::gemm_phase<Epi1, Sched1, true, true>(F.lds, DM, DM, S, E); }
.LBB0_104:
	s_or_b64 exec, exec, s[4:5]
	s_waitcnt lgkmcnt(0)
	v_mov_b32_e32 v1, v0
	s_mov_b64 s[4:5], s[0:1]
	s_barrier
	s_load_dwordx4 s[8:11], s[4:5], 0xa8
	s_load_dwordx4 s[24:27], s[0:1], 0x70
	v_mov_b32_e32 v10, v0
	s_waitcnt lgkmcnt(0)
	s_add_u32 s29, s10, 0x1ba00000
	s_addc_u32 s74, s11, 0
	s_add_u32 s75, s10, 0x1b200000
	s_addc_u32 s76, s11, 0
	s_add_u32 s77, s10, 0x20e00000
	s_addc_u32 s78, s11, 0
	s_add_u32 s79, s10, 0x1fe00000
	s_addc_u32 s80, s11, 0
	s_cmpk_lt_i32 s2, 0xe0
	s_cselect_b64 s[6:7], -1, 0
	s_cmpk_gt_i32 s2, 0xdf
	v_readfirstlane_b32 s12, v10
	s_cbranch_scc1 .LBB0_111
	s_cmp_gt_i32 s2, 15
	s_cbranch_scc0 .LBB0_112
	s_cmpk_gt_u32 s2, 0x4cf
	s_cbranch_scc0 .LBB0_113
	s_cmpk_gt_u32 s2, 0x50b
	s_cbranch_scc0 .LBB0_114
	s_add_i32 s13, s2, 0xfffffaf4
	s_lshr_b32 s16, s13, 4
	s_bfe_u32 s4, s13, 0x20002
	s_and_b32 s62, s2, 3
	s_add_i32 s5, s16, 1
	s_cmp_gt_u32 s13, 15
	s_cbranch_scc0 .LBB0_115
	s_lshl_b32 s18, s4, 21
	s_cmp_lg_u32 s16, 1
	s_cbranch_scc0 .LBB0_116
	s_add_u32 s16, s79, s18
	s_addc_u32 s17, s80, 0
	s_add_u32 s66, s16, 0x800000
	s_addc_u32 s67, s17, 0
	s_lshl_b32 s16, s62, 21
	s_add_u32 s68, s75, s16
	s_addc_u32 s69, s76, 0
	s_mov_b64 s[16:17], 0
	s_branch .LBB0_117

; template <class Epi, class Sched, bool ALIGN_EPI, bool SP2, bool BPRE = false>
; __device__ __forceinline__ void gemm_phase(LAS unsigned char* lds, const int pitchA, const int pitchB, const Sched& S, const Epi& E) {
;     ...
;     for (;;) {
;         const bool has_next = S.next(ui + 1, nxt);
;         const char* nA = has_next ? nxt.A : cA; const char* nB = has_next ? nxt.B : cB;
;     __device__ __forceinline__ bool next(int i, Unit& u) const {
;         int L = i * G + c; if (L >= G1_ALL) return false;
;         u.nt = DM / 64; u.kind = 0;
;         if (L < G1_SPECIAL) { u.pm = MP / 256 + (L >> 3); u.pn = 30 + (L & 7); u.kind = 4; }
;         else if ((L -= G1_SPECIAL) < G1_PROMPT) { int pm, pn; pg8::tile_order(L, MP / 256, G1_NN, pm, pn); u.pm = pm; u.pn = pn; }
;         else if ((L -= G1_PROMPT) < G1_S2) { u.pm = MP / 256 + L / 30; u.pn = L % 30; }
;         else { const int r = L - G1_S2, t = r >> 4, pm = (r >> 2) & 3, pn = r & 3; u.pm = pm; u.pn = pn; u.kind = 1 + t;
;             if (t == 0) { u.A = HM + (size_t)pm * TSTEP4K; u.B = WKV + (size_t)pn * TSTEP4K; }
;             else if (t == 1) { u.A = HM + (size_t)pm * TSTEP4K; u.B = WKV + (size_t)(4 + pn) * TSTEP4K; }
;             else { u.A = WKV + (size_t)(4 + pm) * TSTEP4K; u.B = HM + (size_t)pn * TSTEP4K; }
;             return true; }
;         u.A = H + (size_t)u.pm * TSTEP4K; u.B = WIN + (size_t)u.pn * TSTEP4K;
;         return true;
.LBB0_136:
	s_add_i32 s12, s12, 1
	s_mul_i32 s5, s12, 0xe0
	s_add_i32 s5, s5, s2
	s_cmpk_lt_i32 s5, 0x53c
	s_cselect_b64 s[56:57], -1, 0
	s_cmpk_gt_i32 s5, 0x53b
	s_cbranch_scc1 .LBB0_156
	s_cmp_gt_i32 s5, 15
	s_cbranch_scc0 .LBB0_152
	s_cmpk_gt_u32 s5, 0x4cf
	s_cbranch_scc0 .LBB0_267
	s_cmpk_gt_u32 s5, 0x50b
	s_mov_b64 s[70:71], -1
	s_cbranch_scc0 .LBB0_268
	s_add_i32 s59, s5, 0xfffffaf4
	s_lshr_b32 s63, s59, 4
	s_bfe_u32 s58, s59, 0x20002
	s_and_b32 s60, s5, 3
	s_add_i32 s6, s63, 1
	s_cmp_gt_u32 s59, 15
	s_cbranch_scc0 .LBB0_146
	s_lshl_b32 s61, s58, 21
	s_cmp_lg_u32 s63, 1
	s_cbranch_scc0 .LBB0_143
	s_add_u32 s13, s79, s61
	s_addc_u32 s55, s80, 0
	s_add_u32 s54, s13, 0x800000
	s_addc_u32 s55, s55, 0
	s_lshl_b32 s13, s60, 21
	s_add_u32 s64, s75, s13
	s_addc_u32 s65, s76, 0
	s_mov_b64 s[70:71], 0

; __global__ void __launch_bounds__(NTHR, 2) hybrid_fwd(Args args) {
;     ...
;     if ((int)blockIdx.x >= NAS_FREE_FROM && (int)gridDim.x == 256) {
;         Frame F = make_frame(lds);
;         if (F.tid < 64) { unsigned* fl = (unsigned*)(F.ws + WS_CTL) + CW_QREADY; unsigned sp = 0;
;             while (__hip_atomic_load(fl, __ATOMIC_RELAXED, __HIP_MEMORY_SCOPE_AGENT) < (unsigned)G1_SPECIAL) { __builtin_amdgcn_s_sleep(4); if (++sp > (1u << 22)) break; }
;             __builtin_amdgcn_fence(__ATOMIC_ACQUIRE, "agent"); }
.LBB0_271:
	s_cmp_gt_i32 s2, 0xdf
	s_cselect_b64 s[4:5], -1, 0
	s_and_b64 s[6:7], s[4:5], s[38:39]
	v_cndmask_b32_e64 v1, 0, 1, s[6:7]
	v_cmp_ne_u32_e64 s[4:5], 1, v1
	s_andn2_b64 vcc, exec, s[6:7]
	s_cbranch_vccnz .LBB0_311
	v_mov_b32_e32 v2, v0
	s_mov_b64 s[6:7], s[0:1]
	s_load_dwordx4 s[16:19], s[6:7], 0x18
	s_load_dwordx2 s[10:11], s[6:7], 0xb0
	v_readfirstlane_b32 s12, v2
	v_cmp_gt_i32_e32 vcc, 64, v2
	s_and_saveexec_b64 s[6:7], vcc
	s_cbranch_execz .LBB0_282
	s_waitcnt lgkmcnt(0)
	s_add_u32 s8, s10, 0x8000
	s_addc_u32 s9, s11, 0
	s_mov_b32 s13, 0x400001
	v_mov_b32_e32 v1, 0
	s_branch .LBB0_275

; #define LAS __attribute__((address_space(3)))
; __device__ __forceinline__ float bf_lo(unsigned w) { return __uint_as_float(w << 16); }
; __device__ __forceinline__ float bf_hi(unsigned w) { return __uint_as_float(w & 0xffff0000u); }
; __device__ __forceinline__ void attn_sample_head_unit(Frame& F, int unit) {
;     const int b = unit >> 2, head = unit & 3;
;     unsigned ln = (unsigned)F.lane; asm volatile("" : "+v"(ln));
;     const unsigned hk = ln >> 5, e0 = (ln & 31u) * 4u;
;     const bf16_t* Q = WSP(bf16_t, WS_Q); const bf16_t* SGC = WSP(bf16_t, WS_SGC); bf16_t* CAT = WSP(bf16_t, WS_CAT);
;     LAS float* SL = (LAS float*)F.lds;
;     LAS float* OL = (LAS float*)(F.lds + 4096);
;     float q[4][8];
; #pragma unroll
;     for (int t = 0; t < 4; ++t) { const u32x2 w0 = ldg<u32x2>(Q + (size_t)(MP + b * DS + t) * DX + head * HD, e0 * 2u), w1 = ldg<u32x2>(Q + (size_t)(MP + b * DS + t) * DX + head * HD, (128u + e0) * 2u);
;         q[t][0] = bf_lo(w0.x); q[t][1] = bf_hi(w0.x); q[t][2] = bf_lo(w0.y); q[t][3] = bf_hi(w0.y); q[t][4] = bf_lo(w1.x); q[t][5] = bf_hi(w1.x); q[t][6] = bf_lo(w1.y); q[t][7] = bf_hi(w1.y); }
;     const float* Kc = F.in[3] + (size_t)b * NMEM * DX + head * HD + (size_t)(32 * F.wave) * DX;
;     const float* Vc = F.in[4] + (size_t)b * NMEM * DX + head * HD + (size_t)(32 * F.wave) * DX;
;     const unsigned koff = hk * (DX * 4u) + e0 * 4u;
; __global__ void __launch_bounds__(NTHR, 2) hybrid_fwd(Args args) {
;     ...
;             while (__hip_atomic_load(fl, __ATOMIC_RELAXED, __HIP_MEMORY_SCOPE_AGENT) < (unsigned)G1_SPECIAL) { __builtin_amdgcn_s_sleep(4); if (++sp > (1u << 22)) break; }
;             __builtin_amdgcn_fence(__ATOMIC_ACQUIRE, "agent"); }
;         asm volatile("s_waitcnt vmcnt(0)" ::: "memory"); __syncthreads();
;         for (int u = (int)blockIdx.x - NAS_FREE_FROM; u < NAS_UNITS; u += 256 - NAS_FREE_FROM) attn_sample_head_unit(F, u);
.LBB0_282:
	s_or_b64 exec, exec, s[6:7]
	s_waitcnt vmcnt(0)
	s_cmpk_gt_i32 s2, 0x2df
	s_waitcnt vmcnt(0) lgkmcnt(0)
	s_barrier
	s_cbranch_scc1 .LBB0_311
	s_ashr_i32 s20, s12, 6
	s_lshl_b32 s6, s20, 2
	s_add_i32 s12, s6, 0
	s_sub_i32 s29, s2, 0xe0
	s_add_u32 s13, s10, 0x9200000
	s_addc_u32 s34, s11, 0
	s_add_u32 s22, s10, 0xa300000
	s_addc_u32 s23, s11, 0
	s_lshl_b32 s6, s20, 5
	s_ashr_i32 s7, s6, 31
	s_lshl_b64 s[8:9], s[6:7], 10
	s_lshl_b32 s6, s20, 9
	s_add_i32 s35, s6, 0
	s_cmp_lt_i32 s20, 4
	s_cselect_b64 s[40:41], -1, 0
	s_lshl_b32 s6, s20, 12
	s_add_i32 s36, s6, 0
	s_movk_i32 s6, 0x100
	v_and_b32_e32 v1, 63, v2
	v_cmp_gt_i32_e64 s[6:7], s6, v2
	v_ashrrev_i32_e32 v102, 6, v2
	v_lshlrev_b32_e32 v2, 2, v2
	v_and_b32_e32 v103, 0xfc, v2
	v_lshlrev_b32_e32 v2, 10, v102
	v_lshlrev_b32_e32 v3, 2, v103
	v_add3_u32 v104, 0, v2, v3
	v_mbcnt_lo_u32_b32 v2, -1, 0
	s_mov_b32 s21, 0
	v_mov_b32_e32 v59, 0
	s_mov_b64 s[42:43], 0x1000800
	s_mov_b32 s37, 0x1000000
	s_mov_b64 s[44:45], 0x1001000
	s_mov_b32 s58, 0x1001000
	s_mov_b64 s[46:47], 0x1001800
	s_lshl_b64 s[48:49], s[8:9], 2
	s_mov_b32 s59, 0xff61b1e6
	v_mbcnt_hi_u32_b32 v105, -1, v2
	s_branch .LBB0_285
.LBB0_284:
	s_or_b64 exec, exec, s[8:9]
	s_waitcnt lgkmcnt(0)
	s_add_i32 s8, s29, 0x20
	s_cmpk_lt_i32 s29, 0x1e0
	s_mov_b32 s29, s8
	s_barrier
	s_cbranch_scc0 .LBB0_311

; #define LAS __attribute__((address_space(3)))
; __device__ __forceinline__ void p0_items(Frame& F, int first, int last, int gw, int NGW) {
;     LAS float* scr = (LAS float*)(F.lds + F.wave * 16640);
;     bf16_t* WIN = WSP(bf16_t, WS_WIN); bf16_t* WKV = WSP(bf16_t, WS_WKV); bf16_t* WOUT = WSP(bf16_t, WS_WOUT); bf16_t* WPW = WSP(bf16_t, WS_WPW); bf16_t* WPOOL = WSP(bf16_t, WS_WPOOL);
;     for (int it = first + gw; it < last; it += NGW) {
;         int r = it; const float* src; bf16_t* dst; int ldw, ldt;
;         if (r < I_IN) { const int kb = r / 152, nb = r % 152; src = F.in[9] + (size_t)(64 * kb) * DIN + win_src_col(64 * nb); ldw = DIN; dst = WIN + (size_t)(64 * nb) * DM + 64 * kb; ldt = DM; }
;         else if ((r -= I_IN) < I_KV) { const int kb = r / 16, nb = r % 16; src = F.in[10] + (size_t)(64 * kb) * DX + 64 * nb; ldw = DX; dst = WKV + (size_t)(64 * nb) * DM + 64 * kb; ldt = DM; }
;         else if ((r -= I_KV) < I_KV) { const int kb = r / 16, nb = r % 16; src = F.in[11] + (size_t)(64 * kb) * DX + 64 * nb; ldw = DX; dst = WKV + (size_t)(1024 + 64 * nb) * DM + 64 * kb; ldt = DM; }
;         else if ((r -= I_KV) < I_OUT) { const int kb = r / 64, nb = r % 64; src = F.in[19] + (size_t)(64 * kb) * DM + 64 * nb; ldw = DM; dst = WOUT + (size_t)(64 * nb) * DM + 64 * kb; ldt = DM; }
;         else if ((r -= I_OUT) < I_PW) { const int kb = r / 24, nb = r % 24; src = F.in[18] + (size_t)(64 * kb) * DCONV + 64 * nb; ldw = DCONV; dst = WPW + (size_t)(64 * nb) * DCONV + 64 * kb; ldt = DCONV; }
;         else { r -= I_PW; const int g = r / I_PL, q = r % I_PL, kb = q / 6, nb = q % 6;
;             src = F.in[12] + (size_t)g * PGRP * PGRP + (size_t)(64 * kb) * PGRP + 64 * nb; ldw = PGRP; dst = WPOOL + (size_t)g * 512 * PGRP + (size_t)(64 * nb) * PGRP + 64 * kb; ldt = PGRP; }
;         p0_transpose_item(src, ldw, dst, ldt, scr, F.lane);
; __global__ void __launch_bounds__(NTHR, 2) hybrid_fwd(Args args) {
;     ...
;     {
;         constexpr int NFREE = 256 - NAS_FREE_FROM, N3 = NAS_UNITS - 2 * NFREE, NLATE = NFREE - N3;
;         const int idx = (int)blockIdx.x - NAS_FREE_FROM - N3;
;         if (idx >= 0 && (int)gridDim.x == 256) { Frame F = make_frame(lds);
;             p0_items(F, NITEMS_EARLY, NITEMS, idx * NWAVES + F.wave, NLATE * NWAVES);
;             p0_pool_pad(F, idx * NTHR + F.tid, NLATE * NTHR); p0_pool_frag(F, idx * NTHR + F.tid, NLATE * NTHR); }
.LBB0_311:
	s_cmpk_lt_i32 s2, 0xe0
	s_cselect_b64 s[6:7], -1, 0
	s_xor_b64 s[8:9], s[38:39], -1
	s_or_b64 s[6:7], s[6:7], s[8:9]
	s_and_b64 vcc, exec, s[6:7]
	s_cbranch_vccnz .LBB0_347
	v_mov_b32_e32 v1, v0
	s_mov_b64 s[38:39], s[0:1]
	s_add_i32 s12, s2, 0xffffff20
	v_readfirstlane_b32 s6, v1
	s_ashr_i32 s40, s6, 6
	s_load_dwordx8 s[16:23], s[38:39], 0x48
	s_load_dwordx2 s[6:7], s[38:39], 0xb0
	s_lshl_b32 s8, s12, 3
	s_add_i32 s41, s40, s8
	s_cmpk_gt_i32 s41, 0x12cf
	v_and_b32_e32 v6, 15, v1
	s_cbranch_scc1 .LBB0_340
	s_waitcnt lgkmcnt(0)
	s_add_u32 s13, s6, 0x20e00000
	s_addc_u32 s29, s7, 0
	s_add_u32 s34, s6, 0x1fe00000
	s_addc_u32 s35, s7, 0
	s_add_u32 s36, s6, 0x100000
	s_addc_u32 s37, s7, 0
	s_add_u32 s50, s6, 0x2100000
	s_addc_u32 s51, s7, 0
	s_load_dwordx4 s[8:11], s[38:39], 0x90
	s_add_u32 s52, s6, 0x2600000
	s_mulk_i32 s40, 0x4100
	s_addc_u32 s53, s7, 0
	s_add_i32 s38, s40, 0
	v_bfe_u32 v7, v1, 4, 2
	v_lshlrev_b32_e32 v4, 3, v1
	v_lshl_add_u32 v9, v6, 4, s38
	v_mul_u32_u24_e32 v34, 0x104, v7
	v_bfe_u32 v25, v1, 3, 3
	v_and_b32_e32 v8, 56, v4
	s_add_i32 s54, s41, 0x2e00
	v_lshlrev_b32_e32 v2, 2, v6
	v_mov_b32_e32 v3, 0
	v_mul_u32_u24_e32 v4, 0x104, v8
	v_lshlrev_b32_e32 v5, 2, v25
	v_add_u32_e32 v34, v9, v34
	s_mov_b32 s39, 0
	v_or_b32_e32 v10, 4, v7
	v_or_b32_e32 v11, 8, v7
	v_or_b32_e32 v12, 12, v7
	v_or_b32_e32 v13, 16, v7
	v_or_b32_e32 v14, 20, v7
	v_or_b32_e32 v15, 24, v7
	v_or_b32_e32 v16, 28, v7
	v_or_b32_e32 v17, 32, v7
	v_or_b32_e32 v18, 36, v7
	v_or_b32_e32 v19, 40, v7
	v_or_b32_e32 v20, 44, v7
	v_or_b32_e32 v21, 48, v7
	v_or_b32_e32 v22, 52, v7
	v_or_b32_e32 v23, 56, v7
	v_or_b32_e32 v24, 60, v7
	v_add3_u32 v26, s38, v4, v5
	v_or_b32_e32 v27, 8, v25
	v_or_b32_e32 v28, 16, v25
	v_or_b32_e32 v29, 24, v25
	v_or_b32_e32 v30, 32, v25
	v_or_b32_e32 v31, 40, v25
	v_or_b32_e32 v32, 48, v25
	v_or_b32_e32 v33, 56, v25
	s_lshl_b32 s55, s54, 6
	s_lshl_b32 s56, s54, 2
	v_lshlrev_b32_e32 v4, 2, v2
	v_mov_b32_e32 v5, v3
	v_add_u32_e32 v35, 0x410, v34
	v_add_u32_e32 v36, 0x418, v34
	v_add_u32_e32 v37, 0x820, v34
	v_add_u32_e32 v38, 0x828, v34
	v_add_u32_e32 v39, 0xc30, v34
	v_add_u32_e32 v40, 0xc38, v34
	v_add_u32_e32 v41, 0x1040, v34
	v_add_u32_e32 v42, 0x1048, v34
	v_add_u32_e32 v43, 0x1450, v34
	v_add_u32_e32 v44, 0x1458, v34
	v_add_u32_e32 v45, 0x1860, v34
	v_add_u32_e32 v46, 0x1868, v34
	v_add_u32_e32 v47, 0x1c70, v34
	v_add_u32_e32 v48, 0x1c78, v34
	v_add_u32_e32 v49, 0x2080, v34
	v_add_u32_e32 v50, 0x2088, v34
	v_add_u32_e32 v51, 0x2490, v34
	v_add_u32_e32 v52, 0x2498, v34
	v_add_u32_e32 v53, 0x28a0, v34
	v_add_u32_e32 v54, 0x28a8, v34
	v_add_u32_e32 v55, 0x2cb0, v34
	v_add_u32_e32 v56, 0x2cb8, v34
	v_add_u32_e32 v57, 0x30c0, v34
	v_add_u32_e32 v58, 0x30c8, v34
	v_add_u32_e32 v59, 0x34d0, v34
	v_lshlrev_b32_e32 v8, 1, v8
	v_mov_b32_e32 v9, v3
	v_add_u32_e32 v60, 0x34d8, v34
	v_add_u32_e32 v61, 0x38e0, v34
	s_branch .LBB0_316

; #define LAS __attribute__((address_space(3)))
; #define GAS __attribute__((address_space(1)))
; #define LDS_WAIT() asm volatile("s_waitcnt lgkmcnt(0)" ::: "memory")
; __device__ __forceinline__ unsigned cvt_pk_bf16(float lo, float hi) { unsigned r; asm volatile("v_cvt_pk_bf16_f32 %0, %1, %2" : "=v"(r) : "v"(lo), "v"(hi)); return r; }
; __device__ __forceinline__ void p0_transpose_item(const float* Wsrc  , int ldw, bf16_t* dst  , int ldt, LAS float* scr, int lane) {
;     const int r = lane >> 4, c4 = lane & 15;
;     f32x4 v[16];
; #pragma unroll
;     for (int i = 0; i < 16; ++i) v[i] = __builtin_nontemporal_load((const GAS f32x4*)(Wsrc + (size_t)(4 * i + r) * ldw + 4 * c4));
; #pragma unroll
;     for (int i = 0; i < 16; ++i) { LAS float* s = scr + (4 * i + r) * 65 + 4 * c4; s[0] = v[i].x; s[1] = v[i].y; s[2] = v[i].z; s[3] = v[i].w; }
;     LDS_WAIT(); asm volatile("" ::: "memory");
;     const int c = lane & 7;
; #pragma unroll
;     for (int j = 0; j < 8; ++j) { const int n = (lane >> 3) + 8 * j; const LAS float* s = scr + (8 * c) * 65 + n;
;         u32x4 o; o.x = cvt_pk_bf16(s[0 * 65], s[1 * 65]); o.y = cvt_pk_bf16(s[2 * 65], s[3 * 65]); o.z = cvt_pk_bf16(s[4 * 65], s[5 * 65]); o.w = cvt_pk_bf16(s[6 * 65], s[7 * 65]);
;         *(GAS u32x4*)(dst + (size_t)n * ldt + 8 * c) = o; }
; __device__ __forceinline__ void p0_items(Frame& F, int first, int last, int gw, int NGW) {
;     ...
;     for (int it = first + gw; it < last; it += NGW) {
.LBB0_315:
	v_mul_u32_u24_e32 v2, s46, v7
	v_lshl_add_u64 v[122:123], s[44:45], 0, v[4:5]
	v_lshlrev_b32_e32 v2, 2, v2
	v_lshl_add_u64 v[62:63], v[122:123], 0, v[2:3]
	v_mul_u32_u24_e32 v2, s46, v10
	v_lshlrev_b32_e32 v2, 2, v2
	v_lshl_add_u64 v[66:67], v[122:123], 0, v[2:3]
	v_mul_u32_u24_e32 v2, s46, v11
	v_lshlrev_b32_e32 v2, 2, v2
	v_lshl_add_u64 v[70:71], v[122:123], 0, v[2:3]
	v_mul_u32_u24_e32 v2, s46, v12
	v_lshlrev_b32_e32 v2, 2, v2
	v_lshl_add_u64 v[74:75], v[122:123], 0, v[2:3]
	v_mul_u32_u24_e32 v2, s46, v13
	v_lshlrev_b32_e32 v2, 2, v2
	v_lshl_add_u64 v[78:79], v[122:123], 0, v[2:3]
	v_mul_u32_u24_e32 v2, s46, v14
	v_lshlrev_b32_e32 v2, 2, v2
	v_lshl_add_u64 v[82:83], v[122:123], 0, v[2:3]
	v_mul_u32_u24_e32 v2, s46, v15
	v_lshlrev_b32_e32 v2, 2, v2
	v_lshl_add_u64 v[86:87], v[122:123], 0, v[2:3]
	v_mul_u32_u24_e32 v2, s46, v16
	v_lshlrev_b32_e32 v2, 2, v2
	v_lshl_add_u64 v[90:91], v[122:123], 0, v[2:3]
	v_mul_u32_u24_e32 v2, s46, v17
	v_lshlrev_b32_e32 v2, 2, v2
	v_lshl_add_u64 v[94:95], v[122:123], 0, v[2:3]
	v_mul_u32_u24_e32 v2, s46, v18
	v_lshlrev_b32_e32 v2, 2, v2
	v_lshl_add_u64 v[98:99], v[122:123], 0, v[2:3]
	v_mul_u32_u24_e32 v2, s46, v19
	v_lshlrev_b32_e32 v2, 2, v2
	v_lshl_add_u64 v[102:103], v[122:123], 0, v[2:3]
	v_mul_u32_u24_e32 v2, s46, v20
	v_lshlrev_b32_e32 v2, 2, v2
	v_lshl_add_u64 v[106:107], v[122:123], 0, v[2:3]
	v_mul_u32_u24_e32 v2, s46, v21
	v_lshlrev_b32_e32 v2, 2, v2
	v_lshl_add_u64 v[110:111], v[122:123], 0, v[2:3]
	v_mul_u32_u24_e32 v2, s46, v22
	v_lshlrev_b32_e32 v2, 2, v2
	v_lshl_add_u64 v[114:115], v[122:123], 0, v[2:3]
	global_load_dwordx4 v[62:65], v[62:63], off nt
	s_nop 0
	global_load_dwordx4 v[66:69], v[66:67], off nt
	s_nop 0
	global_load_dwordx4 v[70:73], v[70:71], off nt
	s_nop 0
	global_load_dwordx4 v[74:77], v[74:75], off nt
	s_nop 0
	global_load_dwordx4 v[78:81], v[78:79], off nt
	s_nop 0
	global_load_dwordx4 v[82:85], v[82:83], off nt
	s_nop 0
	global_load_dwordx4 v[86:89], v[86:87], off nt
	s_nop 0
	global_load_dwordx4 v[90:93], v[90:91], off nt
	s_nop 0
	global_load_dwordx4 v[94:97], v[94:95], off nt
	s_nop 0
	global_load_dwordx4 v[98:101], v[98:99], off nt
	s_nop 0
	global_load_dwordx4 v[102:105], v[102:103], off nt
	s_nop 0
	global_load_dwordx4 v[106:109], v[106:107], off nt
	s_nop 0
	global_load_dwordx4 v[110:113], v[110:111], off nt
	s_nop 0
	global_load_dwordx4 v[114:117], v[114:115], off nt
	v_mul_u32_u24_e32 v2, s46, v23
	v_lshlrev_b32_e32 v2, 2, v2
	v_lshl_add_u64 v[118:119], v[122:123], 0, v[2:3]
	v_mul_u32_u24_e32 v2, s46, v24
	global_load_dwordx4 v[118:121], v[118:119], off nt
	v_lshlrev_b32_e32 v2, 2, v2
	v_lshl_add_u64 v[122:123], v[122:123], 0, v[2:3]
	global_load_dwordx4 v[122:125], v[122:123], off nt
	v_add_u32_e32 v2, 0x38e8, v34
	v_add_u32_e32 v126, 0x3cf0, v34
	v_add_u32_e32 v127, 0x3cf8, v34
	s_add_i32 s38, s54, 0x100
	s_add_i32 s55, s55, 0x4000
	s_addk_i32 s56, 0x400
	s_cmpk_lt_i32 s54, 0x3fd0
	s_mov_b32 s54, s38
	s_waitcnt vmcnt(0)
	ds_write2_b32 v34, v62, v63 offset1:1
	ds_write2_b32 v34, v64, v65 offset0:2 offset1:3
	ds_write2_b32 v35, v66, v67 offset1:1
	ds_write2_b32 v36, v68, v69 offset1:1
	ds_write2_b32 v37, v70, v71 offset1:1
	ds_write2_b32 v38, v72, v73 offset1:1
	ds_write2_b32 v39, v74, v75 offset1:1
	ds_write2_b32 v40, v76, v77 offset1:1
	ds_write2_b32 v41, v78, v79 offset1:1
	ds_write2_b32 v42, v80, v81 offset1:1
	ds_write2_b32 v43, v82, v83 offset1:1
	ds_write2_b32 v44, v84, v85 offset1:1
	ds_write2_b32 v45, v86, v87 offset1:1
	ds_write2_b32 v46, v88, v89 offset1:1
	ds_write2_b32 v47, v90, v91 offset1:1
	ds_write2_b32 v48, v92, v93 offset1:1
	ds_write2_b32 v49, v94, v95 offset1:1
	ds_write2_b32 v50, v96, v97 offset1:1
	ds_write2_b32 v51, v98, v99 offset1:1
	ds_write2_b32 v52, v100, v101 offset1:1
	ds_write2_b32 v53, v102, v103 offset1:1
	ds_write2_b32 v54, v104, v105 offset1:1
	ds_write2_b32 v55, v106, v107 offset1:1
	ds_write2_b32 v56, v108, v109 offset1:1
	ds_write2_b32 v57, v110, v111 offset1:1
	ds_write2_b32 v58, v112, v113 offset1:1
	ds_write2_b32 v59, v114, v115 offset1:1
	ds_write2_b32 v60, v116, v117 offset1:1
	ds_write2_b32 v61, v118, v119 offset1:1
	ds_write2_b32 v2, v120, v121 offset1:1
	ds_write2_b32 v126, v122, v123 offset1:1
	ds_write2_b32 v127, v124, v125 offset1:1
	s_waitcnt lgkmcnt(0)
	ds_read2_b32 v[62:63], v26 offset1:65
	s_waitcnt lgkmcnt(0)
	v_cvt_pk_bf16_f32 v62, v62, v63
	ds_read2_b32 v[64:65], v26 offset0:130 offset1:195
	v_add_u32_e32 v72, 0x400, v26
	v_mul_u32_u24_e32 v2, s40, v25
	s_waitcnt lgkmcnt(0)
; #define LAS __attribute__((address_space(3)))
; #define GAS __attribute__((address_space(1)))
; #define LDS_WAIT() asm volatile("s_waitcnt lgkmcnt(0)" ::: "memory")
; __device__ __forceinline__ unsigned cvt_pk_bf16(float lo, float hi) { unsigned r; asm volatile("v_cvt_pk_bf16_f32 %0, %1, %2" : "=v"(r) : "v"(lo), "v"(hi)); return r; }
; __device__ __forceinline__ void p0_transpose_item(const float* Wsrc  , int ldw, bf16_t* dst  , int ldt, LAS float* scr, int lane) {
;     ...
;     const int c = lane & 7;
; #pragma unroll
;     for (int j = 0; j < 8; ++j) { const int n = (lane >> 3) + 8 * j; const LAS float* s = scr + (8 * c) * 65 + n;
;         u32x4 o; o.x = cvt_pk_bf16(s[0 * 65], s[1 * 65]); o.y = cvt_pk_bf16(s[2 * 65], s[3 * 65]); o.z = cvt_pk_bf16(s[4 * 65], s[5 * 65]); o.w = cvt_pk_bf16(s[6 * 65], s[7 * 65]);
;         *(GAS u32x4*)(dst + (size_t)n * ldt + 8 * c) = o; }
;     LDS_WAIT(); asm volatile("" ::: "memory");
	v_cvt_pk_bf16_f32 v63, v64, v65
	ds_read2_b32 v[64:65], v72 offset0:4 offset1:69
	v_lshl_add_u64 v[68:69], s[42:43], 0, v[8:9]
	v_lshlrev_b32_e32 v2, 1, v2
	s_waitcnt lgkmcnt(0)
	v_cvt_pk_bf16_f32 v64, v64, v65
	ds_read2_b32 v[66:67], v72 offset0:134 offset1:199
	s_waitcnt lgkmcnt(0)
	v_cvt_pk_bf16_f32 v65, v66, v67
	v_lshl_add_u64 v[70:71], v[68:69], 0, v[2:3]
	ds_read2_b32 v[66:67], v26 offset0:8 offset1:73
	global_store_dwordx4 v[70:71], v[62:65], off
	v_mul_u32_u24_e32 v2, s40, v27
	v_lshlrev_b32_e32 v2, 1, v2
	s_waitcnt lgkmcnt(0)
	v_cvt_pk_bf16_f32 v62, v66, v67
	ds_read2_b32 v[64:65], v26 offset0:138 offset1:203
	s_waitcnt lgkmcnt(0)
	v_cvt_pk_bf16_f32 v63, v64, v65
	ds_read2_b32 v[64:65], v72 offset0:12 offset1:77
	s_waitcnt lgkmcnt(0)
	v_cvt_pk_bf16_f32 v64, v64, v65
	ds_read2_b32 v[66:67], v72 offset0:142 offset1:207
	s_waitcnt lgkmcnt(0)
	v_cvt_pk_bf16_f32 v65, v66, v67
	v_lshl_add_u64 v[70:71], v[68:69], 0, v[2:3]
	ds_read2_b32 v[66:67], v26 offset0:16 offset1:81
	global_store_dwordx4 v[70:71], v[62:65], off
	v_mul_u32_u24_e32 v2, s40, v28
	v_lshlrev_b32_e32 v2, 1, v2
	s_waitcnt lgkmcnt(0)
	v_cvt_pk_bf16_f32 v62, v66, v67
	ds_read2_b32 v[64:65], v26 offset0:146 offset1:211
	s_waitcnt lgkmcnt(0)
	v_cvt_pk_bf16_f32 v63, v64, v65
	ds_read2_b32 v[64:65], v72 offset0:20 offset1:85
	s_waitcnt lgkmcnt(0)
	v_cvt_pk_bf16_f32 v64, v64, v65
	ds_read2_b32 v[66:67], v72 offset0:150 offset1:215
	s_waitcnt lgkmcnt(0)
	v_cvt_pk_bf16_f32 v65, v66, v67
	v_lshl_add_u64 v[70:71], v[68:69], 0, v[2:3]
	ds_read2_b32 v[66:67], v26 offset0:24 offset1:89
	global_store_dwordx4 v[70:71], v[62:65], off
	v_mul_u32_u24_e32 v2, s40, v29
	v_lshlrev_b32_e32 v2, 1, v2
	s_waitcnt lgkmcnt(0)
	v_cvt_pk_bf16_f32 v62, v66, v67
	ds_read2_b32 v[64:65], v26 offset0:154 offset1:219
	s_waitcnt lgkmcnt(0)
	v_cvt_pk_bf16_f32 v63, v64, v65
	ds_read2_b32 v[64:65], v72 offset0:28 offset1:93
	s_waitcnt lgkmcnt(0)
	v_cvt_pk_bf16_f32 v64, v64, v65
	ds_read2_b32 v[66:67], v72 offset0:158 offset1:223
	s_waitcnt lgkmcnt(0)
	v_cvt_pk_bf16_f32 v65, v66, v67
	v_lshl_add_u64 v[70:71], v[68:69], 0, v[2:3]
	ds_read2_b32 v[66:67], v26 offset0:32 offset1:97
	global_store_dwordx4 v[70:71], v[62:65], off
	v_mul_u32_u24_e32 v2, s40, v30
	v_lshlrev_b32_e32 v2, 1, v2
	s_waitcnt lgkmcnt(0)
	v_cvt_pk_bf16_f32 v62, v66, v67
	ds_read2_b32 v[64:65], v26 offset0:162 offset1:227
	s_waitcnt lgkmcnt(0)
	v_cvt_pk_bf16_f32 v63, v64, v65
	ds_read2_b32 v[64:65], v72 offset0:36 offset1:101
	s_waitcnt lgkmcnt(0)
	v_cvt_pk_bf16_f32 v64, v64, v65
	ds_read2_b32 v[66:67], v72 offset0:166 offset1:231
	s_waitcnt lgkmcnt(0)
	v_cvt_pk_bf16_f32 v65, v66, v67
	v_lshl_add_u64 v[70:71], v[68:69], 0, v[2:3]
	ds_read2_b32 v[66:67], v26 offset0:40 offset1:105
	global_store_dwordx4 v[70:71], v[62:65], off
	v_mul_u32_u24_e32 v2, s40, v31
	v_lshlrev_b32_e32 v2, 1, v2
	s_waitcnt lgkmcnt(0)
	v_cvt_pk_bf16_f32 v62, v66, v67
	ds_read2_b32 v[64:65], v26 offset0:170 offset1:235
	s_waitcnt lgkmcnt(0)
	v_cvt_pk_bf16_f32 v63, v64, v65
	ds_read2_b32 v[64:65], v72 offset0:44 offset1:109
	s_waitcnt lgkmcnt(0)
	v_cvt_pk_bf16_f32 v64, v64, v65
	ds_read2_b32 v[66:67], v72 offset0:174 offset1:239
	s_waitcnt lgkmcnt(0)
	v_cvt_pk_bf16_f32 v65, v66, v67
	v_lshl_add_u64 v[70:71], v[68:69], 0, v[2:3]
	ds_read2_b32 v[66:67], v26 offset0:48 offset1:113
	global_store_dwordx4 v[70:71], v[62:65], off
	v_mul_u32_u24_e32 v2, s40, v32
	v_lshlrev_b32_e32 v2, 1, v2
	s_waitcnt lgkmcnt(0)
	v_cvt_pk_bf16_f32 v62, v66, v67
	ds_read2_b32 v[64:65], v26 offset0:178 offset1:243
	s_waitcnt lgkmcnt(0)
	v_cvt_pk_bf16_f32 v63, v64, v65
	ds_read2_b32 v[64:65], v72 offset0:52 offset1:117
	s_waitcnt lgkmcnt(0)
	v_cvt_pk_bf16_f32 v64, v64, v65
	ds_read2_b32 v[66:67], v72 offset0:182 offset1:247
	s_waitcnt lgkmcnt(0)
	v_cvt_pk_bf16_f32 v65, v66, v67
	v_lshl_add_u64 v[70:71], v[68:69], 0, v[2:3]
	v_mul_u32_u24_e32 v2, s40, v33
	ds_read2_b32 v[66:67], v26 offset0:56 offset1:121
	global_store_dwordx4 v[70:71], v[62:65], off
	v_lshlrev_b32_e32 v2, 1, v2
	v_lshl_add_u64 v[68:69], v[68:69], 0, v[2:3]
	s_waitcnt lgkmcnt(0)
	v_cvt_pk_bf16_f32 v62, v66, v67
	ds_read2_b32 v[64:65], v26 offset0:186 offset1:251
	s_waitcnt lgkmcnt(0)
	v_cvt_pk_bf16_f32 v63, v64, v65
	ds_read2_b32 v[64:65], v72 offset0:60 offset1:125
	s_waitcnt lgkmcnt(0)
	v_cvt_pk_bf16_f32 v64, v64, v65
	ds_read2_b32 v[66:67], v72 offset0:190 offset1:255
	s_waitcnt lgkmcnt(0)
	v_cvt_pk_bf16_f32 v65, v66, v67
	global_store_dwordx4 v[68:69], v[62:65], off
	s_waitcnt lgkmcnt(0)
	s_cbranch_scc0 .LBB0_340

; #define GAS __attribute__((address_space(1)))
; __device__ __forceinline__ unsigned cvt_pk_bf16(float lo, float hi) { unsigned r; asm volatile("v_cvt_pk_bf16_f32 %0, %1, %2" : "=v"(r) : "v"(lo), "v"(hi)); return r; }
; __device__ __forceinline__ void p0_pool_pad(Frame& F, int gt, int NGT) {
;     bf16_t* WPOOL = WSP(bf16_t, WS_WPOOL);
;     for (int i = gt; i < 4 * 6144; i += NGT) { const int g = i / 6144, q = i % 6144; *(GAS u32x4*)(WPOOL + (size_t)g * 512 * PGRP + (size_t)384 * PGRP + (size_t)q * 8) = (u32x4){0u, 0u, 0u, 0u}; }
; }
; __device__ __forceinline__ void p0_pool_frag(Frame& F, int gt, int NGT) {
;     bf16_t* WF = WSP(bf16_t, WS_WPOOLF);
;     for (int i = gt; i < 4 * 24 * 12 * 64; i += NGT) { const int l = i & 63, blk = i >> 6, ks = blk % 12, nt = (blk / 12) % 24, g = blk / 288;
;         const float* src = F.in[12] + (size_t)g * PGRP * PGRP + (size_t)(32 * ks + 8 * (l >> 4)) * PGRP + 16 * nt + (l & 15);
;         float v[8];
; #pragma unroll
;         for (int e = 0; e < 8; ++e) v[e] = *(const GAS float*)(src + (size_t)e * PGRP);
;         *(GAS u32x4*)(WF + (size_t)i * 8) = (u32x4){cvt_pk_bf16(v[0], v[1]), cvt_pk_bf16(v[2], v[3]), cvt_pk_bf16(v[4], v[5]), cvt_pk_bf16(v[6], v[7])}; }
; }
.LBB0_340:
	v_lshl_add_u32 v8, s12, 9, v1
	s_movk_i32 s8, 0x6000
	v_cmp_gt_i32_e32 vcc, s8, v8
	s_and_saveexec_b64 s[8:9], vcc
	s_cbranch_execz .LBB0_343
	v_mov_b32_e32 v2, 0
	s_mov_b64 s[10:11], 0
	s_mov_b32 s12, 0x2aaaaaab
	v_mov_b32_e32 v3, v2
	v_mov_b32_e32 v4, v2
	v_mov_b32_e32 v5, v2
	s_movk_i32 s13, 0x1fff
	v_mov_b32_e32 v7, v8
.LBB0_342:
	v_mul_hi_i32 v9, v7, s12
	v_lshrrev_b32_e32 v10, 31, v9
	v_ashrrev_i32_e32 v9, 10, v9
	v_add_u32_e32 v9, v9, v10
	v_mul_i32_i24_e32 v12, 0x1800, v9
	v_add_u32_e32 v13, 0x4000, v7
	v_mul_hi_i32_i24_e32 v11, 0x60000, v9
	v_mul_i32_i24_e32 v10, 0x60000, v9
	v_sub_u32_e32 v12, v7, v12
	v_cmp_lt_i32_e32 vcc, s13, v7
	s_waitcnt lgkmcnt(0)
	v_lshl_add_u64 v[10:11], s[6:7], 0, v[10:11]
	v_mov_b32_e32 v7, v13
	v_ashrrev_i32_e32 v13, 31, v12
	v_lshl_add_u64 v[10:11], v[12:13], 4, v[10:11]
	s_or_b64 s[10:11], vcc, s[10:11]
	v_add_co_u32_e32 v10, vcc, 0x2648000, v10
	s_nop 1
	v_addc_co_u32_e32 v11, vcc, 0, v11, vcc
	global_store_dwordx4 v[10:11], v[2:5], off
	s_andn2_b64 exec, exec, s[10:11]
	s_cbranch_execnz .LBB0_342
.LBB0_343:
	s_or_b64 exec, exec, s[8:9]
	s_mov_b32 s8, 0x12000
	v_cmp_gt_i32_e32 vcc, s8, v8
	s_and_saveexec_b64 s[8:9], vcc
	s_cbranch_execz .LBB0_346
	v_ashrrev_i32_e32 v9, 31, v8
	v_lshl_add_u32 v1, s2, 9, v1
	s_waitcnt lgkmcnt(0)
	v_lshl_add_u64 v[4:5], v[8:9], 4, s[6:7]
	s_mov_b64 s[6:7], 0x2800000
	v_mov_b32_e32 v3, 0
	v_add_u32_e32 v1, 0xfffe0000, v1
	v_lshl_add_u64 v[4:5], v[4:5], 0, s[6:7]
	s_mov_b64 s[6:7], 0
	s_mov_b32 s12, 0x2aaaaaab
	s_mov_b32 s13, 0x38e38e39
	s_movk_i32 s16, 0x180
	s_movk_i32 s17, 0x600
	v_mov_b64_e32 v[8:9], s[22:23]
	v_lshlrev_b32_e32 v2, 2, v6
	s_movk_i32 s18, 0x1000
	s_movk_i32 s19, 0x2000
	s_mov_b64 s[10:11], 0x40000
	s_mov_b32 s20, 0xdfff
.LBB0_345:
	v_add_u32_e32 v1, 0x4000, v1
	v_ashrrev_i32_e32 v6, 6, v1
	v_lshrrev_b32_e32 v7, 1, v1
	v_mul_hi_i32 v10, v6, s12
	v_mul_hi_i32 v11, v6, s13
	v_and_b32_e32 v12, 24, v7
	v_lshrrev_b32_e32 v7, 31, v10
	v_ashrrev_i32_e32 v10, 1, v10
	v_lshrrev_b32_e32 v13, 31, v11
	v_lshrrev_b32_e32 v11, 6, v11
	v_add_u32_e32 v14, v10, v7
	v_add_u32_e32 v7, v11, v13
	v_mul_lo_u32 v10, v14, 12
	v_mul_hi_i32 v11, v14, s12
	v_sub_u32_e32 v10, v6, v10
	v_lshrrev_b32_e32 v13, 31, v11
	v_lshrrev_b32_e32 v11, 2, v11
	v_add_u32_e32 v11, v11, v13
	v_lshl_or_b32 v10, v10, 5, v12
	v_mul_i32_i24_e32 v7, 0x180, v7
	v_mul_lo_u32 v11, v11, 24
	v_mul_lo_u32 v10, v10, s16
	v_mad_i64_i32 v[6:7], s[22:23], v7, s17, v[8:9]
	v_sub_u32_e32 v12, v14, v11
	v_ashrrev_i32_e32 v11, 31, v10
	v_lshl_add_u64 v[6:7], v[10:11], 2, v[6:7]
	v_lshlrev_b32_e32 v10, 4, v12
	v_ashrrev_i32_e32 v11, 31, v10
	v_lshl_add_u64 v[6:7], v[10:11], 2, v[6:7]
	v_lshl_add_u64 v[6:7], v[6:7], 0, v[2:3]
	v_add_co_u32_e32 v10, vcc, s18, v6
	global_load_dword v14, v[6:7], off offset:1536
	s_nop 0
	v_addc_co_u32_e32 v11, vcc, 0, v7, vcc
	v_add_co_u32_e32 v12, vcc, s19, v6
	s_nop 1
	v_addc_co_u32_e32 v13, vcc, 0, v7, vcc
	global_load_dword v15, v[10:11], off offset:512
	global_load_dword v16, v[10:11], off offset:3584
	global_load_dword v17, v[12:13], off offset:1024
	global_load_dword v18, v[12:13], off offset:2560
	global_load_dword v19, v[10:11], off offset:2048
	global_load_dword v20, v[6:7], off offset:3072
	global_load_dword v21, v[6:7], off
	v_cmp_lt_i32_e32 vcc, s20, v1
	s_or_b64 s[6:7], vcc, s[6:7]
	s_waitcnt vmcnt(0)
	v_cvt_pk_bf16_f32 v10, v21, v14
	v_cvt_pk_bf16_f32 v11, v20, v15
	v_cvt_pk_bf16_f32 v12, v19, v16
	v_cvt_pk_bf16_f32 v13, v17, v18
	global_store_dwordx4 v[4:5], v[10:13], off
	v_lshl_add_u64 v[4:5], v[4:5], 0, s[10:11]
	s_andn2_b64 exec, exec, s[6:7]
	s_cbranch_execnz .LBB0_345

; #define GAS __attribute__((address_space(1)))
; __device__ __forceinline__ void states_copy_rows(Frame& F, int gw, int NGW) {
;     constexpr int KP_ = PSTATE - DS, KC_ = CSTATE - DS, R_P = DB * KP_, R_C = DB * KC_;
;     const unsigned ln = (unsigned)F.lane;
;     for (int i = gw; i < R_P + R_C; i += NGW) {
;         const float* sf; float* dst;
;         if (i < R_P) { const int b = i / KP_, j = i % KP_; sf = F.in[5] + (size_t)(b * PSTATE + j + DS) * DPOOL; dst = F.out + O_PSS + (size_t)(b * PSTATE + j) * DPOOL; }
;         else { const int r = i - R_P, b = r / KC_, j = r % KC_; sf = F.in[6] + (size_t)(b * CSTATE + j + DS) * DCONV; dst = F.out + O_CSS + (size_t)(b * CSTATE + j) * DCONV; }
;         f32x4 v[6];
; #pragma unroll
;         for (int k = 0; k < 6; ++k) v[k] = ldg<f32x4>(sf, (256u * k + 4u * ln) * 4u);
; #pragma unroll
;         for (int k = 0; k < 6; ++k) *(GAS f32x4*)((char*)dst + (256u * k + 4u * ln) * 4u) = v[k];
;     }
; }
; __global__ void __launch_bounds__(NTHR, 2) hybrid_fwd(Args args) {
;     ...
;     if ((int)blockIdx.x >= NAS_FREE_FROM && (int)gridDim.x == 256) {
;         Frame F = make_frame(lds); states_copy_rows(F, ((int)blockIdx.x - NAS_FREE_FROM) * NWAVES + F.wave, (256 - NAS_FREE_FROM) * NWAVES); }
.LBB0_347:
	s_and_b64 vcc, exec, s[4:5]
	s_cbranch_vccnz .LBB0_355
	v_mov_b32_e32 v1, v0
	s_lshl_b32 s5, s2, 3
	v_readfirstlane_b32 s4, v1
	s_ashr_i32 s4, s4, 6
	s_add_i32 s4, s5, s4
	s_add_i32 s12, s4, 0xfffff900
	s_mov_b64 s[8:9], s[0:1]
	s_cmpk_gt_i32 s12, 0x127f
	s_cbranch_scc1 .LBB0_355
	s_waitcnt lgkmcnt(0)
	s_load_dwordx4 s[4:7], s[8:9], 0x28
	s_load_dwordx2 s[10:11], s[8:9], 0xa8
	v_lshlrev_b32_e32 v1, 4, v1
	v_and_b32_e32 v2, 0x3f0, v1
	v_mov_b32_e32 v3, 0
	v_or_b32_e32 v4, 0x1000, v2
	s_waitcnt lgkmcnt(0)
	s_add_u32 s13, s10, 0x9c4e000
	s_addc_u32 s18, s11, 0
	s_add_u32 s19, s10, 0x910e000
	v_mov_b32_e32 v5, v3
	v_or_b32_e32 v6, 0x1400, v2
	v_mov_b32_e32 v7, v3
	s_addc_u32 s20, s11, 0
	s_branch .LBB0_351
.LBB0_350:
	v_lshl_add_u64 v[24:25], s[10:11], 0, v[2:3]
	v_lshl_add_u64 v[32:33], s[10:11], 0, v[4:5]
	global_load_dwordx4 v[8:11], v[24:25], off
	global_load_dwordx4 v[12:15], v[24:25], off offset:1024
	global_load_dwordx4 v[16:19], v[24:25], off offset:2048
	global_load_dwordx4 v[20:23], v[24:25], off offset:3072
	v_lshl_add_u64 v[34:35], s[10:11], 0, v[6:7]
	global_load_dwordx4 v[24:27], v[32:33], off
	global_load_dwordx4 v[28:31], v[34:35], off
	v_lshl_add_u64 v[32:33], s[8:9], 0, v[2:3]
	v_lshl_add_u64 v[34:35], s[8:9], 0, v[4:5]
	v_lshl_add_u64 v[36:37], s[8:9], 0, v[6:7]
	s_add_i32 s8, s12, 0x100
	s_cmpk_lt_i32 s12, 0x1180
	s_mov_b32 s12, s8
	s_waitcnt vmcnt(0)
	global_store_dwordx4 v[32:33], v[8:11], off
	global_store_dwordx4 v[32:33], v[12:15], off offset:1024
	global_store_dwordx4 v[32:33], v[16:19], off offset:2048
	global_store_dwordx4 v[32:33], v[20:23], off offset:3072
	global_store_dwordx4 v[34:35], v[24:27], off
	global_store_dwordx4 v[36:37], v[28:31], off
	s_cbranch_scc0 .LBB0_355
